# retention O block staged through a wave-private 2 KiB slice of 16 KiB extra static LDS and stored with 2 dwordx4 per lane instead of 16 short stores
# baseline (speedup 1.0000x reference)
.LBB0_61:
	v_add_u32_e32 v0, v166, v133
	ds_read_b128 v[2:5], v165
	ds_read_b128 v[6:9], v165 offset:32
	ds_read_b128 v[10:13], v0
	ds_read_b128 v[140:143], v0 offset:32
	s_add_i32 s66, s66, s98
	s_ashr_i32 s67, s66, 31
	s_waitcnt lgkmcnt(1)
	v_mfma_f32_32x32x16_bf16 v[48:63], v[2:5], v[10:13], 0
	s_lshl_b64 s[4:5], s[66:67], 11
	s_add_u32 s66, s76, s4
	s_addc_u32 s67, s77, s5
	v_readlane_b32 s4, v254, 8
	v_mul_f32_e64 v16, v136, v16
	v_mul_f32_e64 v17, v137, v17
	s_add_i32 s14, s14, -1
	s_add_i32 s33, s33, 1
	s_waitcnt lgkmcnt(0)
	v_mfma_f32_32x32x16_bf16 v[48:63], v[6:9], v[140:143], v[48:63]
	ds_read_b128 v[2:5], v165 offset:64
	ds_read_b128 v[6:9], v0 offset:64
	s_cmp_eq_u32 s14, -1
	s_waitcnt lgkmcnt(0)
	v_mfma_f32_32x32x16_bf16 v[48:63], v[2:5], v[6:9], v[48:63]
	ds_read_b128 v[2:5], v165 offset:96
	ds_read_b128 v[6:9], v0 offset:96
	s_waitcnt lgkmcnt(0)
	v_mfma_f32_32x32x16_bf16 v[48:63], v[2:5], v[6:9], v[48:63]
	ds_read_b128 v[2:5], v165 offset:128
	ds_read_b128 v[6:9], v0 offset:128
	s_waitcnt lgkmcnt(0)
	v_mfma_f32_32x32x16_bf16 v[48:63], v[2:5], v[6:9], v[48:63]
	ds_read_b128 v[2:5], v165 offset:160
	ds_read_b128 v[6:9], v0 offset:160
	s_waitcnt lgkmcnt(0)
	v_mfma_f32_32x32x16_bf16 v[48:63], v[2:5], v[6:9], v[48:63]
	ds_read_b128 v[2:5], v165 offset:192
	ds_read_b128 v[6:9], v0 offset:192
	s_waitcnt lgkmcnt(0)
	v_mfma_f32_32x32x16_bf16 v[48:63], v[2:5], v[6:9], v[48:63]
	ds_read_b128 v[2:5], v165 offset:224
	ds_read_b128 v[6:9], v0 offset:224
	s_nop 0
	v_lshl_add_u32 v0, v164, 2, s18
	s_waitcnt lgkmcnt(0)
	v_mfma_f32_32x32x16_bf16 v[48:63], v[2:5], v[6:9], v[48:63]
	v_lshl_add_u32 v2, v0, 2, 0
	v_add_u32_e32 v6, 0x22200, v2
	ds_read_b128 v[8:11], v6
	ds_read_b128 v[2:5], v6 offset:32
	v_add_u32_e32 v7, s17, v135
	v_lshl_add_u32 v0, v0, 10, v7
	v_lshlrev_b32_e32 v236, 1, v135
	v_lshl_add_u32 v236, v164, 8, v236
	v_mov_b32_e32 v135, v134
	v_mbcnt_lo_u32_b32 v237, -1, 0
	v_mbcnt_hi_u32_b32 v237, -1, v237
	v_mov_b32_e32 v241, 0x24000
	v_lshl_add_u32 v241, s18, 7, v241
	v_lshl_add_u32 v241, s17, 6, v241
	v_add_u32_e32 v236, v241, v236
	v_lshl_add_u32 v238, v237, 4, v241
	v_lshrrev_b32_e32 v239, 2, v237
	v_and_b32_e32 v237, 3, v237
	v_lshlrev_b32_e32 v237, 4, v237
	v_lshl_add_u32 v239, v239, 11, v237
	v_lshl_add_u32 v239, s18, 11, v239
	v_lshl_add_u32 v239, s17, 1, v239
	v_add_u32_e32 v240, 0x8000, v239
	s_waitcnt lgkmcnt(1)
	s_nop 2
	v_fma_f32 v244, v48, v8, v32
	v_fma_f32 v245, v49, v9, v33
	v_cvt_pk_bf16_f32 v244, v244, v245
	ds_write_b16 v236, v244
	ds_write_b16_d16_hi v236, v244 offset:64
	v_fma_f32 v246, v50, v10, v34
	v_fma_f32 v247, v51, v11, v35
	v_cvt_pk_bf16_f32 v246, v246, v247
	ds_write_b16 v236, v246 offset:128
	ds_write_b16_d16_hi v236, v246 offset:192
	s_waitcnt lgkmcnt(0)
	v_fma_f32 v244, v52, v2, v36
	v_fma_f32 v245, v53, v3, v37
	v_cvt_pk_bf16_f32 v244, v244, v245
	ds_write_b16 v236, v244 offset:512
	ds_write_b16_d16_hi v236, v244 offset:576
	v_fma_f32 v246, v54, v4, v38
	v_fma_f32 v247, v55, v5, v39
	v_cvt_pk_bf16_f32 v246, v246, v247
	ds_write_b16 v236, v246 offset:640
	ds_write_b16_d16_hi v236, v246 offset:704
	ds_read_b128 v[2:5], v6 offset:64
	v_pk_mul_f32 v[30:31], v[134:135], v[30:31]
	s_waitcnt lgkmcnt(0)
	v_fma_f32 v244, v56, v2, v40
	v_fma_f32 v245, v57, v3, v41
	v_cvt_pk_bf16_f32 v244, v244, v245
	ds_write_b16 v236, v244 offset:1024
	ds_write_b16_d16_hi v236, v244 offset:1088
	v_fma_f32 v246, v58, v4, v42
	v_fma_f32 v247, v59, v5, v43
	v_cvt_pk_bf16_f32 v246, v246, v247
	ds_write_b16 v236, v246 offset:1152
	ds_write_b16_d16_hi v236, v246 offset:1216
	ds_read_b128 v[2:5], v6 offset:96
	v_pk_mul_f32 v[28:29], v[134:135], v[28:29]
	s_waitcnt lgkmcnt(0)
	v_fma_f32 v244, v60, v2, v44
	v_fma_f32 v245, v61, v3, v45
	v_cvt_pk_bf16_f32 v244, v244, v245
	ds_write_b16 v236, v244 offset:1536
	ds_write_b16_d16_hi v236, v244 offset:1600
	v_fma_f32 v246, v62, v4, v46
	v_fma_f32 v247, v63, v5, v47
	v_cvt_pk_bf16_f32 v246, v246, v247
	ds_write_b16 v236, v246 offset:1664
	ds_write_b16_d16_hi v236, v246 offset:1728
	ds_read_b128 v[248:251], v238
	ds_read_b128 v[226:229], v238 offset:1024
	s_waitcnt lgkmcnt(1)
	global_store_dwordx4 v239, v[248:251], s[66:67]
	s_waitcnt lgkmcnt(0)
	global_store_dwordx4 v240, v[226:229], s[66:67]
	v_add3_u32 v0, s4, v163, v133
	ds_read_b128 v[2:5], v0
	ds_read_b128 v[6:9], v0 offset:32
	ds_read_b128 v[10:13], v138
	ds_read_b128 v[32:35], v138 offset:32
	v_pk_mul_f32 v[26:27], v[134:135], v[26:27]
	v_pk_mul_f32 v[24:25], v[134:135], v[24:25]
	v_pk_mul_f32 v[22:23], v[134:135], v[22:23]
	v_pk_mul_f32 v[20:21], v[134:135], v[20:21]
	v_pk_mul_f32 v[18:19], v[134:135], v[18:19]
	s_waitcnt lgkmcnt(1)
	s_nop 0
	v_mfma_f32_32x32x16_bf16 v[16:31], v[2:5], v[10:13], v[16:31]
	s_waitcnt lgkmcnt(0)
	v_mfma_f32_32x32x16_bf16 v[16:31], v[6:9], v[32:35], v[16:31]
	ds_read_b128 v[2:5], v0 offset:64
	ds_read_b128 v[6:9], v138 offset:64
	s_waitcnt lgkmcnt(0)
	v_mfma_f32_32x32x16_bf16 v[16:31], v[2:5], v[6:9], v[16:31]
	ds_read_b128 v[2:5], v0 offset:96
	ds_read_b128 v[6:9], v138 offset:96
	s_waitcnt lgkmcnt(0)
	v_mfma_f32_32x32x16_bf16 v[16:31], v[2:5], v[6:9], v[16:31]
	ds_read_b128 v[2:5], v0 offset:128
	ds_read_b128 v[6:9], v138 offset:128
	s_waitcnt lgkmcnt(0)
	v_mfma_f32_32x32x16_bf16 v[16:31], v[2:5], v[6:9], v[16:31]
	ds_read_b128 v[2:5], v0 offset:160
	ds_read_b128 v[6:9], v138 offset:160
	s_waitcnt lgkmcnt(0)
	v_mfma_f32_32x32x16_bf16 v[16:31], v[2:5], v[6:9], v[16:31]
	ds_read_b128 v[2:5], v0 offset:192
	ds_read_b128 v[6:9], v138 offset:192
	s_waitcnt lgkmcnt(0)
	v_mfma_f32_32x32x16_bf16 v[16:31], v[2:5], v[6:9], v[16:31]
	ds_read_b128 v[2:5], v0 offset:224
	ds_read_b128 v[6:9], v138 offset:224
	s_waitcnt lgkmcnt(0)
	s_barrier
	v_mfma_f32_32x32x16_bf16 v[16:31], v[2:5], v[6:9], v[16:31]
	s_cbranch_scc1 .LBB0_92

	.amdhsa_kernel _Z14fwd_megakernel6Params
		.amdhsa_group_segment_fixed_size 16384
		.amdhsa_private_segment_fixed_size 0
		.amdhsa_kernarg_size 464
		.amdhsa_user_sgpr_count 2
		.amdhsa_user_sgpr_dispatch_ptr 0
		.amdhsa_user_sgpr_queue_ptr 0
		.amdhsa_user_sgpr_kernarg_segment_ptr 1
		.amdhsa_user_sgpr_dispatch_id 0
		.amdhsa_user_sgpr_kernarg_preload_length 0
		.amdhsa_user_sgpr_kernarg_preload_offset 0
		.amdhsa_user_sgpr_private_segment_size 0
		.amdhsa_uses_dynamic_stack 0
		.amdhsa_enable_private_segment 0
		.amdhsa_system_sgpr_workgroup_id_x 1
		.amdhsa_system_sgpr_workgroup_id_y 0
		.amdhsa_system_sgpr_workgroup_id_z 0
		.amdhsa_system_sgpr_workgroup_info 0
		.amdhsa_system_vgpr_workitem_id 2
		.amdhsa_next_free_vgpr 256
		.amdhsa_next_free_sgpr 100
		.amdhsa_accum_offset 256
		.amdhsa_reserve_vcc 1
		.amdhsa_float_round_mode_32 0
		.amdhsa_float_round_mode_16_64 0
		.amdhsa_float_denorm_mode_32 3
		.amdhsa_float_denorm_mode_16_64 3
		.amdhsa_dx10_clamp 1
		.amdhsa_ieee_mode 1
		.amdhsa_fp16_overflow 0
		.amdhsa_tg_split 0
		.amdhsa_exception_fp_ieee_invalid_op 0
		.amdhsa_exception_fp_denorm_src 0
		.amdhsa_exception_fp_ieee_div_zero 0
		.amdhsa_exception_fp_ieee_overflow 0
		.amdhsa_exception_fp_ieee_underflow 0
		.amdhsa_exception_fp_ieee_inexact 0
		.amdhsa_exception_int_div_zero 0
	.end_amdhsa_kernel

amdhsa.kernels:
  - .agpr_count:     0
    .args:
      - .offset:         0
        .size:           208
        .value_kind:     by_value
      - .offset:         208
        .size:           4
        .value_kind:     hidden_block_count_x
      - .offset:         212
        .size:           4
        .value_kind:     hidden_block_count_y
      - .offset:         216
        .size:           4
        .value_kind:     hidden_block_count_z
      - .offset:         220
        .size:           2
        .value_kind:     hidden_group_size_x
      - .offset:         222
        .size:           2
        .value_kind:     hidden_group_size_y
      - .offset:         224
        .size:           2
        .value_kind:     hidden_group_size_z
      - .offset:         226
        .size:           2
        .value_kind:     hidden_remainder_x
      - .offset:         228
        .size:           2
        .value_kind:     hidden_remainder_y
      - .offset:         230
        .size:           2
        .value_kind:     hidden_remainder_z
      - .offset:         248
        .size:           8
        .value_kind:     hidden_global_offset_x
      - .offset:         256
        .size:           8
        .value_kind:     hidden_global_offset_y
      - .offset:         264
        .size:           8
        .value_kind:     hidden_global_offset_z
      - .offset:         272
        .size:           2
        .value_kind:     hidden_grid_dims
      - .offset:         296
        .size:           8
        .value_kind:     hidden_multigrid_sync_arg
      - .offset:         328
        .size:           4
        .value_kind:     hidden_dynamic_lds_size
    .group_segment_fixed_size: 16384
    .kernarg_segment_align: 8
    .kernarg_segment_size: 464
    .language:       OpenCL C
    .language_version:
      - 2
      - 0
    .max_flat_workgroup_size: 512
    .name:           _Z14fwd_megakernel6Params
    .private_segment_fixed_size: 0
    .sgpr_count:     106
    .sgpr_spill_count: 223
    .symbol:         _Z14fwd_megakernel6Params.kd
    .uniform_work_group_size: 1
    .uses_dynamic_stack: false
    .vgpr_count:     256
    .vgpr_spill_count: 0
    .wavefront_size: 64
